# cache_k bf16 conversion moved from P0 into P1 tail (96 WGs without an 11th tile), 8 chunks in flight per wave
# speedup vs baseline: 1.0158x; 1.0011x over previous
; __global__ void __launch_bounds__(512, 2) mk_fwd(Args a) {
;     ...
;         for (size_t i = (size_t)gw; i < (size_t)DBATCH * PAST * 1024 / 512; i += NGW) {
;             const float* s = a.in[I_CK] + i * 512 + lane * 8; const f32x4 v0 = *(const f32x4*)s, v1 = *(const f32x4*)(s + 4);
;             store_bf8(KC + i * 512 + lane * 8, v0, v1);
;         }
.LBB0_415:
	s_waitcnt vmcnt(0)
	v_readlane_b32 s96, v250, 16
	v_readlane_b32 s94, v250, 12
	v_readlane_b32 s10, v250, 14
	v_readlane_b32 s97, v250, 17
	v_readlane_b32 s95, v250, 13
	v_readlane_b32 s11, v250, 15
	s_barrier
	s_cmp_eq_u32 s3, 0x100
	s_cbranch_scc0 .Ltail_done
	s_cmp_ge_u32 s2, 0xa0
	s_cbranch_scc0 .Ltail_done
	v_readlane_b32 s0, v250, 0
	v_readlane_b32 s1, v250, 1
	s_nop 3
	s_sub_u32 s0, s0, 0xd0
	s_subb_u32 s1, s1, 0
	s_load_dwordx2 s[4:5], s[0:1], 0x10
	s_add_u32 s6, s68, 0x16b00000
	s_addc_u32 s7, s69, 0
	s_lshl_b32 s8, s2, 3
	v_readfirstlane_b32 s9, v179
	s_nop 3
	s_lshr_b32 s9, s9, 6
	s_add_u32 s8, s8, s9
	s_sub_u32 s8, s8, 0x500
	s_waitcnt lgkmcnt(0)
	v_lshlrev_b32_e32 v0, 5, v220
	v_lshlrev_b32_e32 v1, 4, v220
	s_mov_b32 s18, s8
.Lkc_loop:
	s_cmp_lt_u32 s18, 0x8000
	s_cbranch_scc0 .Ltail_done
	s_add_u32 s19, s18, 0x0
	s_cmp_lt_u32 s19, 0x8000
	s_cselect_b32 s19, s19, s18
	s_lshl_b32 s32, s19, 11
	s_add_u32 s34, s4, s32
	s_addc_u32 s35, s5, 0
	global_load_dwordx4 v[4:7], v0, s[34:35]
	global_load_dwordx4 v[8:11], v0, s[34:35] offset:16
	s_add_u32 s19, s18, 0x300
	s_cmp_lt_u32 s19, 0x8000
	s_cselect_b32 s19, s19, s18
	s_lshl_b32 s32, s19, 11
	s_add_u32 s34, s4, s32
	s_addc_u32 s35, s5, 0
	global_load_dwordx4 v[12:15], v0, s[34:35]
	global_load_dwordx4 v[16:19], v0, s[34:35] offset:16
	s_add_u32 s19, s18, 0x600
	s_cmp_lt_u32 s19, 0x8000
	s_cselect_b32 s19, s19, s18
	s_lshl_b32 s32, s19, 11
	s_add_u32 s34, s4, s32
	s_addc_u32 s35, s5, 0
	global_load_dwordx4 v[20:23], v0, s[34:35]
	global_load_dwordx4 v[24:27], v0, s[34:35] offset:16
	s_add_u32 s19, s18, 0x900
	s_cmp_lt_u32 s19, 0x8000
	s_cselect_b32 s19, s19, s18
	s_lshl_b32 s32, s19, 11
	s_add_u32 s34, s4, s32
	s_addc_u32 s35, s5, 0
	global_load_dwordx4 v[28:31], v0, s[34:35]
	global_load_dwordx4 v[32:35], v0, s[34:35] offset:16
	s_add_u32 s19, s18, 0xc00
	s_cmp_lt_u32 s19, 0x8000
	s_cselect_b32 s19, s19, s18
	s_lshl_b32 s32, s19, 11
	s_add_u32 s34, s4, s32
	s_addc_u32 s35, s5, 0
	global_load_dwordx4 v[40:43], v0, s[34:35]
	global_load_dwordx4 v[44:47], v0, s[34:35] offset:16
	s_add_u32 s19, s18, 0xf00
	s_cmp_lt_u32 s19, 0x8000
	s_cselect_b32 s19, s19, s18
	s_lshl_b32 s32, s19, 11
	s_add_u32 s34, s4, s32
	s_addc_u32 s35, s5, 0
	global_load_dwordx4 v[48:51], v0, s[34:35]
	global_load_dwordx4 v[52:55], v0, s[34:35] offset:16
	s_add_u32 s19, s18, 0x1200
	s_cmp_lt_u32 s19, 0x8000
	s_cselect_b32 s19, s19, s18
	s_lshl_b32 s32, s19, 11
	s_add_u32 s34, s4, s32
	s_addc_u32 s35, s5, 0
	global_load_dwordx4 v[56:59], v0, s[34:35]
	global_load_dwordx4 v[60:63], v0, s[34:35] offset:16
	s_add_u32 s19, s18, 0x1500
	s_cmp_lt_u32 s19, 0x8000
	s_cselect_b32 s19, s19, s18
	s_lshl_b32 s32, s19, 11
	s_add_u32 s34, s4, s32
	s_addc_u32 s35, s5, 0
	global_load_dwordx4 v[64:67], v0, s[34:35]
	global_load_dwordx4 v[68:71], v0, s[34:35] offset:16
	s_waitcnt vmcnt(14)
	v_cvt_pk_bf16_f32 v72, v4, v5
	v_cvt_pk_bf16_f32 v73, v6, v7
	v_cvt_pk_bf16_f32 v74, v8, v9
	v_cvt_pk_bf16_f32 v75, v10, v11
	s_add_u32 s19, s18, 0x0
	s_cmp_lt_u32 s19, 0x8000
	s_cselect_b32 s19, s19, s18
	s_lshl_b32 s32, s19, 10
	s_add_u32 s36, s6, s32
	s_addc_u32 s37, s7, 0
	global_store_dwordx4 v1, v[72:75], s[36:37]
	s_waitcnt vmcnt(13)
	v_cvt_pk_bf16_f32 v96, v12, v13
	v_cvt_pk_bf16_f32 v97, v14, v15
	v_cvt_pk_bf16_f32 v98, v16, v17
	v_cvt_pk_bf16_f32 v99, v18, v19
	s_add_u32 s19, s18, 0x300
	s_cmp_lt_u32 s19, 0x8000
	s_cselect_b32 s19, s19, s18
	s_lshl_b32 s32, s19, 10
	s_add_u32 s36, s6, s32
	s_addc_u32 s37, s7, 0
	global_store_dwordx4 v1, v[96:99], s[36:37]
	s_waitcnt vmcnt(12)
	v_cvt_pk_bf16_f32 v100, v20, v21
	v_cvt_pk_bf16_f32 v101, v22, v23
	v_cvt_pk_bf16_f32 v102, v24, v25
	v_cvt_pk_bf16_f32 v103, v26, v27
	s_add_u32 s19, s18, 0x600
	s_cmp_lt_u32 s19, 0x8000
	s_cselect_b32 s19, s19, s18
	s_lshl_b32 s32, s19, 10
	s_add_u32 s36, s6, s32
	s_addc_u32 s37, s7, 0
	global_store_dwordx4 v1, v[100:103], s[36:37]
	s_waitcnt vmcnt(11)
	v_cvt_pk_bf16_f32 v104, v28, v29
	v_cvt_pk_bf16_f32 v105, v30, v31
	v_cvt_pk_bf16_f32 v106, v32, v33
	v_cvt_pk_bf16_f32 v107, v34, v35
	s_add_u32 s19, s18, 0x900
	s_cmp_lt_u32 s19, 0x8000
	s_cselect_b32 s19, s19, s18
	s_lshl_b32 s32, s19, 10
	s_add_u32 s36, s6, s32
	s_addc_u32 s37, s7, 0
	global_store_dwordx4 v1, v[104:107], s[36:37]
	s_waitcnt vmcnt(10)
	v_cvt_pk_bf16_f32 v108, v40, v41
	v_cvt_pk_bf16_f32 v109, v42, v43
	v_cvt_pk_bf16_f32 v110, v44, v45
	v_cvt_pk_bf16_f32 v111, v46, v47
	s_add_u32 s19, s18, 0xc00
	s_cmp_lt_u32 s19, 0x8000
	s_cselect_b32 s19, s19, s18
	s_lshl_b32 s32, s19, 10
	s_add_u32 s36, s6, s32
	s_addc_u32 s37, s7, 0
	global_store_dwordx4 v1, v[108:111], s[36:37]
	s_waitcnt vmcnt(9)
	v_cvt_pk_bf16_f32 v112, v48, v49
	v_cvt_pk_bf16_f32 v113, v50, v51
	v_cvt_pk_bf16_f32 v114, v52, v53
	v_cvt_pk_bf16_f32 v115, v54, v55
	s_add_u32 s19, s18, 0xf00
	s_cmp_lt_u32 s19, 0x8000
	s_cselect_b32 s19, s19, s18
	s_lshl_b32 s32, s19, 10
	s_add_u32 s36, s6, s32
	s_addc_u32 s37, s7, 0
	global_store_dwordx4 v1, v[112:115], s[36:37]
	s_waitcnt vmcnt(8)
	v_cvt_pk_bf16_f32 v116, v56, v57
	v_cvt_pk_bf16_f32 v117, v58, v59
	v_cvt_pk_bf16_f32 v118, v60, v61
	v_cvt_pk_bf16_f32 v119, v62, v63
	s_add_u32 s19, s18, 0x1200
	s_cmp_lt_u32 s19, 0x8000
	s_cselect_b32 s19, s19, s18
	s_lshl_b32 s32, s19, 10
	s_add_u32 s36, s6, s32
	s_addc_u32 s37, s7, 0
	global_store_dwordx4 v1, v[116:119], s[36:37]
	s_waitcnt vmcnt(7)
	v_cvt_pk_bf16_f32 v120, v64, v65
	v_cvt_pk_bf16_f32 v121, v66, v67
	v_cvt_pk_bf16_f32 v122, v68, v69
	v_cvt_pk_bf16_f32 v123, v70, v71
	s_add_u32 s19, s18, 0x1500
	s_cmp_lt_u32 s19, 0x8000
	s_cselect_b32 s19, s19, s18
	s_lshl_b32 s32, s19, 10
	s_add_u32 s36, s6, s32
	s_addc_u32 s37, s7, 0
	global_store_dwordx4 v1, v[120:123], s[36:37]
	s_add_u32 s18, s18, 0x1800
	s_branch .Lkc_loop
